# mem_attn: K and V^T fragments loaded 21 MFMAs ahead from a buffer-quad ring (counted vmcnt) instead of load-wait-MFMA per fragment
# baseline (speedup 1.0000x reference)
; __device__ __forceinline__ float ozero() { float z = 0.f; asm volatile("" : "+v"(z)); return z; }
; __device__ __forceinline__ int otid() { return otid_full() & 255; }
; __device__ __forceinline__ f32x4 mfma16(bf16x8 a, bf16x8 b, f32x4 c) { return __builtin_amdgcn_mfma_f32_16x16x32_bf16(a, b, c, 0, 0, 0); }
; __device__ __forceinline__ void mem_attn(const Params& p, int layer, int task) {
;   const int tid = otid(), lane = tid & 63, h = tid >> 6;
;   const int n16 = lane & 15, kq = lane >> 4;
;   const size_t tok0 = (size_t)task * 16; const int b = (int)(tok0 >> 14);
;   const bf* mk = p.MK + (((size_t)layer * 2 + b) * 4 + h) * 256 * 64;
;   const bf* mvt = p.MVT + (((size_t)layer * 2 + b) * 4 + h) * 64 * 256;
;   bf16x8 qf[2];
;   {
;     const bf* qp = p.P + (tok0 + n16) * PW + C_MEQ + h * 64 + 8 * kq;
;     qf[0] = *(const bf16x8*)qp; qf[1] = *(const bf16x8*)(qp + 32);
;   }
;   f32x4 st[16];
; #pragma unroll
;   for (int kb = 0; kb < 16; kb++) {
;     const bf* kp = mk + (size_t)(16 * kb + n16) * 64 + 8 * kq;
;     bf16x8 a0 = *(const bf16x8*)kp, a1 = *(const bf16x8*)(kp + 32);
;     const float z_ = ozero(); f32x4 acc = {z_, z_, z_, z_};
;     acc = mfma16(a0, qf[0], acc); acc = mfma16(a1, qf[1], acc);
;     st[kb] = acc * 0.125f;
;   }
.LBB0_472:
	s_cmpk_gt_i32 s31, 0x1ff
	s_mov_b64 s[0:1], -1
	s_cbranch_scc0 .LBB0_480
	s_cmpk_gt_u32 s31, 0x9ff
	s_cbranch_scc0 .LBB0_475
	s_add_i32 s0, s31, 0xfffff600
	s_lshr_b32 s1, s0, 8
	v_mov_b32_e32 v2, v203
	s_and_b32 s1, s1, 4
	s_or_b32 s1, s1, s27
	v_lshrrev_b32_e32 v0, 6, v2
	v_readlane_b32 s52, v253, 3
	v_and_b32_e32 v83, 15, v2
	v_and_or_b32 v0, v0, 3, s1
	v_readlane_b32 s62, v253, 13
	v_readlane_b32 s63, v253, 14
	v_bfe_u32 v3, v2, 4, 2
	v_lshlrev_b32_e32 v144, 15, v0
	v_lshl_or_b32 v82, s0, 4, v83
	v_mov_b64_e32 v[0:1], s[62:63]
	v_and_b32_e32 v2, 0xc0, v2
	v_readlane_b32 s4, v253, 22
	v_mad_u64_u32 v[0:1], s[0:1], v82, s96, v[0:1]
	v_lshlrev_b32_e32 v16, 1, v2
	v_mov_b32_e32 v17, v145
	v_readlane_b32 s6, v253, 24
	v_readlane_b32 s7, v253, 25
	v_lshlrev_b32_e32 v10, 4, v3
	v_mov_b32_e32 v11, v145
	v_lshl_add_u64 v[20:21], v[0:1], 0, v[16:17]
	v_lshl_add_u64 v[8:9], s[6:7], 0, v[144:145]
	v_lshl_add_u64 v[0:1], v[20:21], 0, v[10:11]
	s_mov_b64 s[0:1], 0x28c0
	s_movk_i32 s2, 0x2000
	v_lshlrev_b32_e32 v18, 3, v3
	v_lshl_add_u64 v[2:3], v[0:1], 0, s[0:1]
	v_add_co_u32_e32 v0, vcc, s2, v0
	v_lshl_add_u64 v[8:9], v[8:9], 0, v[10:11]
	v_lshlrev_b32_e32 v10, 7, v83
	v_addc_co_u32_e32 v1, vcc, 0, v1, vcc
	v_lshl_add_u64 v[8:9], v[8:9], 0, v[10:11]
	global_load_dwordx4 v[4:7], v[0:1], off offset:2240
	s_nop 0
	global_load_dwordx4 v[0:3], v[2:3], off offset:64
	s_nop 0
	v_mov_b32_e32 v104, 0x1000
	v_mov_b32_e32 v105, 0
	v_lshl_add_u64 v[146:147], v[8:9], 0, v[104:105]
	v_mov_b32_e32 v104, 0x2000
	v_lshl_add_u64 v[196:197], v[146:147], 0, v[104:105]
	v_lshl_add_u64 v[198:199], v[196:197], 0, v[104:105]
	v_lshl_add_u64 v[200:201], v[198:199], 0, v[104:105]
	global_load_dwordx4 v[108:111], v[146:147], off offset:-4096
	global_load_dwordx4 v[112:115], v[146:147], off offset:-4032
	global_load_dwordx4 v[116:119], v[146:147], off offset:-2048
	global_load_dwordx4 v[120:123], v[146:147], off offset:-1984
	global_load_dwordx4 v[124:127], v[146:147], off
	global_load_dwordx4 v[128:131], v[146:147], off offset:64
	global_load_dwordx4 v[132:135], v[146:147], off offset:2048
	global_load_dwordx4 v[136:139], v[146:147], off offset:2112
	global_load_dwordx4 v[140:143], v[196:197], off offset:-4096
	global_load_dwordx4 v[148:151], v[196:197], off offset:-4032
	global_load_dwordx4 v[152:155], v[196:197], off offset:-2048
	global_load_dwordx4 v[156:159], v[196:197], off offset:-1984
	global_load_dwordx4 v[160:163], v[196:197], off
	global_load_dwordx4 v[164:167], v[196:197], off offset:64
	global_load_dwordx4 v[168:171], v[196:197], off offset:2048
	global_load_dwordx4 v[172:175], v[196:197], off offset:2112
	global_load_dwordx4 v[176:179], v[198:199], off offset:-4096
	global_load_dwordx4 v[180:183], v[198:199], off offset:-4032
	global_load_dwordx4 v[184:187], v[198:199], off offset:-2048
	global_load_dwordx4 v[188:191], v[198:199], off offset:-1984
	global_load_dwordx4 v[192:195], v[198:199], off
	v_mov_b32_e32 v26, v145
	s_mov_b32 s6, 0x3e000000
	v_mov_b32_e32 v27, v26
	v_mov_b32_e32 v28, v26
	v_mov_b32_e32 v29, v26
	v_mov_b32_e32 v32, v145
	s_movk_i32 s4, 0x1000
	v_add_co_u32_e32 v14, vcc, s4, v8
	v_mov_b32_e32 v38, v145
	s_nop 0
	v_addc_co_u32_e32 v15, vcc, 0, v9, vcc
	v_add_co_u32_e32 v48, vcc, s2, v8
	v_mov_b32_e32 v44, v145
	s_nop 0
	v_addc_co_u32_e32 v49, vcc, 0, v9, vcc
	s_movk_i32 s0, 0x3000
	v_add_co_u32_e32 v54, vcc, s0, v8
	s_movk_i32 s0, 0x4000
	s_nop 0
	v_addc_co_u32_e32 v55, vcc, 0, v9, vcc
	v_mov_b32_e32 v56, v145
	v_mov_b32_e32 v64, v145
	v_mov_b32_e32 v72, v145
	v_readlane_b32 s8, v253, 26
	v_readlane_b32 s9, v253, 27
	v_mov_b32_e32 v19, v145
	s_mov_b32 s3, 0xffff
	v_readlane_b32 s64, v253, 15
	v_readlane_b32 s65, v253, 16
	v_readlane_b32 s5, v253, 23
	v_readlane_b32 s10, v253, 28
	v_readlane_b32 s11, v253, 29
	v_readlane_b32 s12, v253, 30
	v_readlane_b32 s13, v253, 31
	v_readlane_b32 s14, v253, 32
	v_readlane_b32 s15, v253, 33
	v_readlane_b32 s16, v253, 34
	v_readlane_b32 s17, v253, 35
	v_readlane_b32 s18, v253, 36
	v_readlane_b32 s19, v253, 37
	v_readlane_b32 s53, v253, 4
	v_readlane_b32 s54, v253, 5
	v_readlane_b32 s55, v253, 6
	v_readlane_b32 s56, v253, 7
	s_waitcnt vmcnt(20)
	v_mfma_f32_16x16x32_bf16 v[10:13], v[108:111], v[4:7], v[26:29]
	global_load_dwordx4 v[108:111], v[198:199], off offset:64
	v_readlane_b32 s57, v253, 8
	v_readlane_b32 s58, v253, 9
	v_readlane_b32 s59, v253, 10
	s_waitcnt vmcnt(20)
	v_mfma_f32_16x16x32_bf16 v[10:13], v[112:115], v[0:3], v[10:13]
	global_load_dwordx4 v[112:115], v[198:199], off offset:2048
	v_readlane_b32 s60, v253, 11
	v_readlane_b32 s61, v253, 12
	v_readlane_b32 s66, v253, 17
	v_readlane_b32 s67, v253, 18
	s_nop 3
	v_pk_mul_f32 v[22:23], v[12:13], s[6:7] op_sel_hi:[1,0]
	v_pk_mul_f32 v[26:27], v[10:11], s[6:7] op_sel_hi:[1,0]
	s_nop 0
	v_mov_b32_e32 v33, v32
	v_mov_b32_e32 v34, v32
	v_mov_b32_e32 v35, v32
	s_nop 0
	s_waitcnt vmcnt(20)
	v_mfma_f32_16x16x32_bf16 v[10:13], v[116:119], v[4:7], v[32:35]
	global_load_dwordx4 v[116:119], v[198:199], off offset:2112
	s_nop 2
	v_mov_b32_e32 v34, v145
	s_waitcnt vmcnt(20)
	v_mfma_f32_16x16x32_bf16 v[10:13], v[120:123], v[0:3], v[10:13]
	global_load_dwordx4 v[120:123], v[200:201], off offset:-4096
	s_nop 7
	v_pk_mul_f32 v[24:25], v[12:13], s[6:7] op_sel_hi:[1,0]
	v_pk_mul_f32 v[28:29], v[10:11], s[6:7] op_sel_hi:[1,0]
	s_nop 0
	v_mov_b32_e32 v35, v34
	v_mov_b32_e32 v36, v34
	v_mov_b32_e32 v37, v34
	s_nop 0
	s_waitcnt vmcnt(20)
	v_mfma_f32_16x16x32_bf16 v[10:13], v[124:127], v[4:7], v[34:37]
	global_load_dwordx4 v[124:127], v[200:201], off offset:-4032
	s_waitcnt vmcnt(20)
; __device__ __forceinline__ float ozero() { float z = 0.f; asm volatile("" : "+v"(z)); return z; }
; __device__ __forceinline__ f32x4 mfma16(bf16x8 a, bf16x8 b, f32x4 c) { return __builtin_amdgcn_mfma_f32_16x16x32_bf16(a, b, c, 0, 0, 0); }
; __device__ __forceinline__ void mem_attn(const Params& p, int layer, int task) {
;     ...
; #pragma unroll
;   for (int kb = 0; kb < 16; kb++) {
;     const bf* kp = mk + (size_t)(16 * kb + n16) * 64 + 8 * kq;
;     bf16x8 a0 = *(const bf16x8*)kp, a1 = *(const bf16x8*)(kp + 32);
;     const float z_ = ozero(); f32x4 acc = {z_, z_, z_, z_};
;     acc = mfma16(a0, qf[0], acc); acc = mfma16(a1, qf[1], acc);
;     st[kb] = acc * 0.125f;
;   }
	v_mfma_f32_16x16x32_bf16 v[10:13], v[128:131], v[0:3], v[10:13]
	global_load_dwordx4 v[128:131], v[200:201], off offset:-2048
	s_nop 7
	v_pk_mul_f32 v[30:31], v[12:13], s[6:7] op_sel_hi:[1,0]
	v_pk_mul_f32 v[36:37], v[10:11], s[6:7] op_sel_hi:[1,0]
	s_nop 0
	v_mov_b32_e32 v39, v38
	v_mov_b32_e32 v40, v38
	v_mov_b32_e32 v41, v38
	s_nop 0
	s_waitcnt vmcnt(20)
	v_mfma_f32_16x16x32_bf16 v[10:13], v[132:135], v[4:7], v[38:41]
	global_load_dwordx4 v[132:135], v[200:201], off offset:-1984
	s_waitcnt vmcnt(20)
	v_mfma_f32_16x16x32_bf16 v[10:13], v[136:139], v[0:3], v[10:13]
	global_load_dwordx4 v[136:139], v[200:201], off
	s_nop 7
	v_pk_mul_f32 v[32:33], v[12:13], s[6:7] op_sel_hi:[1,0]
	v_pk_mul_f32 v[38:39], v[10:11], s[6:7] op_sel_hi:[1,0]
	s_nop 0
	v_mov_b32_e32 v45, v44
	v_mov_b32_e32 v46, v44
	v_mov_b32_e32 v47, v44
	s_nop 0
	s_waitcnt vmcnt(20)
	v_mfma_f32_16x16x32_bf16 v[10:13], v[140:143], v[4:7], v[44:47]
	global_load_dwordx4 v[140:143], v[200:201], off offset:64
	s_waitcnt vmcnt(20)
	v_mfma_f32_16x16x32_bf16 v[10:13], v[148:151], v[0:3], v[10:13]
	global_load_dwordx4 v[148:151], v[200:201], off offset:2048
	s_nop 7
	v_pk_mul_f32 v[34:35], v[12:13], s[6:7] op_sel_hi:[1,0]
	v_pk_mul_f32 v[42:43], v[10:11], s[6:7] op_sel_hi:[1,0]
	v_mov_b32_e32 v48, v145
	s_nop 0
	v_mov_b32_e32 v49, v48
	v_mov_b32_e32 v50, v48
	v_mov_b32_e32 v51, v48
	s_nop 0
	s_waitcnt vmcnt(20)
	v_mfma_f32_16x16x32_bf16 v[10:13], v[152:155], v[4:7], v[48:51]
	global_load_dwordx4 v[152:155], v[200:201], off offset:2112
	s_nop 2
	v_mov_b32_e32 v50, v145
	s_waitcnt vmcnt(20)
	v_mfma_f32_16x16x32_bf16 v[10:13], v[156:159], v[0:3], v[10:13]
	s_nop 7
	v_pk_mul_f32 v[44:45], v[10:11], s[6:7] op_sel_hi:[1,0]
	v_add_co_u32_e32 v10, vcc, s0, v8
	v_pk_mul_f32 v[40:41], v[12:13], s[6:7] op_sel_hi:[1,0]
	s_nop 0
	v_addc_co_u32_e32 v11, vcc, 0, v9, vcc
	s_movk_i32 s0, 0x6000
	v_mov_b32_e32 v51, v50
	v_mov_b32_e32 v52, v50
	v_mov_b32_e32 v53, v50
	s_nop 0
	s_waitcnt vmcnt(19)
	v_mfma_f32_16x16x32_bf16 v[12:15], v[160:163], v[4:7], v[50:53]
	s_waitcnt vmcnt(18)
	v_mfma_f32_16x16x32_bf16 v[12:15], v[164:167], v[0:3], v[12:15]
	s_nop 7
	v_pk_mul_f32 v[46:47], v[14:15], s[6:7] op_sel_hi:[1,0]
	v_pk_mul_f32 v[50:51], v[12:13], s[6:7] op_sel_hi:[1,0]
	s_nop 0
	s_nop 0
	v_mov_b32_e32 v57, v56
	v_mov_b32_e32 v58, v56
	v_mov_b32_e32 v59, v56
	s_nop 0
	s_waitcnt vmcnt(17)
	v_mfma_f32_16x16x32_bf16 v[12:15], v[168:171], v[4:7], v[56:59]
	s_nop 2
	v_mov_b32_e32 v58, v145
	s_waitcnt vmcnt(16)
	v_mfma_f32_16x16x32_bf16 v[12:15], v[172:175], v[0:3], v[12:15]
	s_nop 7
	v_pk_mul_f32 v[48:49], v[14:15], s[6:7] op_sel_hi:[1,0]
	v_pk_mul_f32 v[52:53], v[12:13], s[6:7] op_sel_hi:[1,0]
	s_nop 0
	v_mov_b32_e32 v59, v58
	v_mov_b32_e32 v60, v58
	v_mov_b32_e32 v61, v58
	s_nop 0
	s_waitcnt vmcnt(15)
	v_mfma_f32_16x16x32_bf16 v[12:15], v[176:179], v[4:7], v[58:61]
	s_waitcnt vmcnt(14)
	v_mfma_f32_16x16x32_bf16 v[12:15], v[180:183], v[0:3], v[12:15]
	s_nop 7
	v_pk_mul_f32 v[54:55], v[14:15], s[6:7] op_sel_hi:[1,0]
	v_pk_mul_f32 v[58:59], v[12:13], s[6:7] op_sel_hi:[1,0]
	s_nop 0
	v_mov_b32_e32 v65, v64
	v_mov_b32_e32 v66, v64
	v_mov_b32_e32 v67, v64
	s_nop 0
	s_waitcnt vmcnt(13)
	v_mfma_f32_16x16x32_bf16 v[10:13], v[184:187], v[4:7], v[64:67]
	v_add_co_u32_e32 v14, vcc, s43, v8
	s_nop 1
	v_mov_b32_e32 v66, v145
	s_waitcnt vmcnt(12)
	v_mfma_f32_16x16x32_bf16 v[10:13], v[188:191], v[0:3], v[10:13]
	v_addc_co_u32_e32 v15, vcc, 0, v9, vcc
	v_add_co_u32_e32 v78, vcc, s0, v8
	s_mov_b32 s0, 0xff61b1e6
	s_nop 0
	v_addc_co_u32_e32 v79, vcc, 0, v9, vcc
	s_nop 2
	v_pk_mul_f32 v[56:57], v[12:13], s[6:7] op_sel_hi:[1,0]
	v_pk_mul_f32 v[60:61], v[10:11], s[6:7] op_sel_hi:[1,0]
	v_add_co_u32_e32 v84, vcc, s47, v8
	v_mov_b32_e32 v67, v66
	v_mov_b32_e32 v68, v66
	v_mov_b32_e32 v69, v66
	v_addc_co_u32_e32 v85, vcc, 0, v9, vcc
	s_waitcnt vmcnt(11)
	v_mfma_f32_16x16x32_bf16 v[10:13], v[192:195], v[4:7], v[66:69]
	s_waitcnt vmcnt(10)
	v_mfma_f32_16x16x32_bf16 v[10:13], v[108:111], v[0:3], v[10:13]
	s_nop 7
	v_pk_mul_f32 v[62:63], v[12:13], s[6:7] op_sel_hi:[1,0]
	v_pk_mul_f32 v[66:67], v[10:11], s[6:7] op_sel_hi:[1,0]
	s_nop 0
	v_mov_b32_e32 v73, v72
	v_mov_b32_e32 v74, v72
	v_mov_b32_e32 v75, v72
	s_nop 0
	s_waitcnt vmcnt(9)
	v_mfma_f32_16x16x32_bf16 v[10:13], v[112:115], v[4:7], v[72:75]
	s_nop 2
	v_mov_b32_e32 v74, v145
	s_waitcnt vmcnt(8)
	v_mfma_f32_16x16x32_bf16 v[10:13], v[116:119], v[0:3], v[10:13]
	s_nop 7
	v_pk_mul_f32 v[64:65], v[12:13], s[6:7] op_sel_hi:[1,0]
	v_pk_mul_f32 v[68:69], v[10:11], s[6:7] op_sel_hi:[1,0]
	s_nop 0
	v_mov_b32_e32 v75, v74
	v_mov_b32_e32 v76, v74
	v_mov_b32_e32 v77, v74
	s_nop 0
	s_waitcnt vmcnt(7)
	v_mfma_f32_16x16x32_bf16 v[10:13], v[120:123], v[4:7], v[74:77]
	s_waitcnt vmcnt(6)
	v_mfma_f32_16x16x32_bf16 v[10:13], v[124:127], v[0:3], v[10:13]
	s_nop 7
	v_pk_mul_f32 v[70:71], v[12:13], s[6:7] op_sel_hi:[1,0]
	v_pk_mul_f32 v[72:73], v[10:11], s[6:7] op_sel_hi:[1,0]
	v_mov_b32_e32 v78, v145
	s_nop 0
	v_mov_b32_e32 v79, v78
	v_mov_b32_e32 v80, v78
	v_mov_b32_e32 v81, v78
	s_nop 0
	s_waitcnt vmcnt(5)
	v_mfma_f32_16x16x32_bf16 v[10:13], v[128:131], v[4:7], v[78:81]
	s_nop 2
	v_mov_b32_e32 v78, v145
	s_waitcnt vmcnt(4)
	v_mfma_f32_16x16x32_bf16 v[10:13], v[132:135], v[0:3], v[10:13]
	s_nop 7
	v_pk_mul_f32 v[74:75], v[12:13], s[6:7] op_sel_hi:[1,0]
	v_pk_mul_f32 v[76:77], v[10:11], s[6:7] op_sel_hi:[1,0]
	s_nop 0
	v_mov_b32_e32 v79, v78
	v_mov_b32_e32 v80, v78
	v_mov_b32_e32 v81, v78
	s_nop 0
	s_waitcnt vmcnt(3)
	v_mfma_f32_16x16x32_bf16 v[8:11], v[136:139], v[4:7], v[78:81]
	s_waitcnt vmcnt(2)
; __device__ __forceinline__ f32x4 mfma16(bf16x8 a, bf16x8 b, f32x4 c) { return __builtin_amdgcn_mfma_f32_16x16x32_bf16(a, b, c, 0, 0, 0); }
; __device__ __forceinline__ void mem_attn(const Params& p, int layer, int task) {
;     ...
;     acc = mfma16(a0, qf[0], acc); acc = mfma16(a1, qf[1], acc);
;     st[kb] = acc * 0.125f;
;   }
;   float mx = -3.0e38f;
; #pragma unroll
;   for (int kb = 0; kb < 16; kb++)
; #pragma unroll
;     for (int r = 0; r < 4; r++) mx = fmaxf(mx, st[kb][r]);
;   mx = fmaxf(mx, __shfl_xor(mx, 16)); mx = fmaxf(mx, __shfl_xor(mx, 32));
;   float sum = 0.f;
; #pragma unroll
;   for (int kb = 0; kb < 16; kb++)
; #pragma unroll
;     for (int r = 0; r < 4; r++) { float e = __expf(st[kb][r] - mx); st[kb][r] = e; sum += e; }
	v_mfma_f32_16x16x32_bf16 v[8:11], v[140:143], v[0:3], v[8:11]
	s_nop 7
	v_pk_mul_f32 v[78:79], v[10:11], s[6:7] op_sel_hi:[1,0]
	v_pk_mul_f32 v[80:81], v[8:9], s[6:7] op_sel_hi:[1,0]
	v_mov_b32_e32 v84, v145
	s_nop 0
	v_mov_b32_e32 v85, v84
	v_mov_b32_e32 v86, v84
	v_mov_b32_e32 v87, v84
	s_nop 0
	s_waitcnt vmcnt(1)
	v_mfma_f32_16x16x32_bf16 v[4:7], v[148:151], v[4:7], v[84:87]
	s_waitcnt vmcnt(0)
	v_mfma_f32_16x16x32_bf16 v[2:5], v[152:155], v[0:3], v[4:7]
	s_nop 5
	v_and_b32_e32 v6, 64, v202
	v_add_u32_e32 v7, 64, v6
	v_pk_mul_f32 v[0:1], v[4:5], s[6:7] op_sel_hi:[1,0]
	v_max3_f32 v4, v26, s0, v27
	v_max3_f32 v4, v4, v22, v23
	v_max3_f32 v4, v4, v28, v29
	v_max3_f32 v4, v4, v24, v25
	v_max3_f32 v4, v4, v36, v37
	v_max3_f32 v4, v4, v30, v31
	v_max3_f32 v4, v4, v38, v39
	v_max3_f32 v4, v4, v32, v33
	v_max3_f32 v4, v4, v42, v43
	v_max3_f32 v4, v4, v34, v35
	v_max3_f32 v4, v4, v44, v45
	v_max3_f32 v4, v4, v40, v41
	v_max3_f32 v4, v4, v50, v51
	v_max3_f32 v4, v4, v46, v47
	v_max3_f32 v4, v4, v52, v53
	v_max3_f32 v4, v4, v48, v49
	v_max3_f32 v4, v4, v58, v59
	v_max3_f32 v4, v4, v54, v55
	v_max3_f32 v4, v4, v60, v61
	v_max3_f32 v4, v4, v56, v57
	v_max3_f32 v4, v4, v66, v67
	v_max3_f32 v4, v4, v62, v63
	v_max3_f32 v4, v4, v68, v69
	v_max3_f32 v4, v4, v64, v65
	v_max3_f32 v4, v4, v72, v73
	v_max3_f32 v4, v4, v70, v71
	v_max3_f32 v4, v4, v76, v77
	v_max3_f32 v4, v4, v74, v75
	v_max3_f32 v4, v4, v80, v81
	v_xor_b32_e32 v5, 16, v202
	v_pk_mul_f32 v[2:3], v[2:3], s[6:7] op_sel_hi:[1,0]
	v_max3_f32 v4, v4, v78, v79
	v_cmp_lt_i32_e32 vcc, v5, v7
	v_max3_f32 v4, v4, v2, v3
	v_max3_f32 v4, v4, v0, v1
	v_cndmask_b32_e32 v5, v202, v5, vcc
	v_lshlrev_b32_e32 v6, 2, v5
	ds_bpermute_b32 v5, v6, v4
	s_mov_b64 s[0:1], 0xc0
	s_waitcnt lgkmcnt(0)
	v_max_f32_e32 v5, v5, v5
	v_max_f32_e32 v4, v4, v5
	v_xor_b32_e32 v5, 32, v202
	v_cmp_lt_i32_e32 vcc, v5, v7
	s_nop 1
	v_cndmask_b32_e32 v5, v202, v5, vcc
	v_lshlrev_b32_e32 v7, 2, v5
	ds_bpermute_b32 v5, v7, v4
	s_waitcnt lgkmcnt(0)
	v_max_f32_e32 v5, v5, v5
	v_max_f32_e32 v15, v4, v5
	v_sub_f32_e32 v9, v22, v15
	v_mul_f32_e32 v9, 0x3fb8aa3b, v9
	v_exp_f32_e32 v93, v9
	v_sub_f32_e32 v9, v23, v15
	v_mul_f32_e32 v9, 0x3fb8aa3b, v9
	v_exp_f32_e32 v95, v9
	v_sub_f32_e32 v9, v28, v15
	v_mul_f32_e32 v9, 0x3fb8aa3b, v9
	v_exp_f32_e32 v96, v9
	v_sub_f32_e32 v9, v29, v15
	v_mul_f32_e32 v9, 0x3fb8aa3b, v9
	v_exp_f32_e32 v99, v9
	v_sub_f32_e32 v9, v24, v15
	v_mul_f32_e32 v9, 0x3fb8aa3b, v9
	v_exp_f32_e32 v101, v9
	v_sub_f32_e32 v9, v25, v15
	v_mul_f32_e32 v9, 0x3fb8aa3b, v9
	v_exp_f32_e32 v103, v9
	v_sub_f32_e32 v9, v36, v15
	v_mul_f32_e32 v9, 0x3fb8aa3b, v9
	v_exp_f32_e32 v94, v9
	v_sub_f32_e32 v9, v37, v15
	v_mul_f32_e32 v9, 0x3fb8aa3b, v9
	v_exp_f32_e32 v97, v9
	v_sub_f32_e32 v9, v30, v15
	v_mul_f32_e32 v9, 0x3fb8aa3b, v9
	v_exp_f32_e32 v98, v9
	v_sub_f32_e32 v9, v31, v15
	v_mul_f32_e32 v9, 0x3fb8aa3b, v9
	v_exp_f32_e32 v100, v9
	v_sub_f32_e32 v9, v38, v15
	v_mul_f32_e32 v9, 0x3fb8aa3b, v9
	v_exp_f32_e32 v102, v9
	v_sub_f32_e32 v9, v39, v15
	v_mul_f32_e32 v9, 0x3fb8aa3b, v9
	v_exp_f32_e32 v104, v9
	v_sub_f32_e32 v9, v32, v15
	v_mul_f32_e32 v9, 0x3fb8aa3b, v9
	v_exp_f32_e32 v105, v9
	v_sub_f32_e32 v9, v33, v15
	v_mul_f32_e32 v9, 0x3fb8aa3b, v9
	v_exp_f32_e32 v106, v9
	v_sub_f32_e32 v9, v42, v15
	v_mul_f32_e32 v9, 0x3fb8aa3b, v9
	v_exp_f32_e32 v85, v9
	v_sub_f32_e32 v9, v43, v15
	v_mul_f32_e32 v9, 0x3fb8aa3b, v9
	v_exp_f32_e32 v86, v9
	v_sub_f32_e32 v9, v34, v15
	v_mul_f32_e32 v9, 0x3fb8aa3b, v9
	v_exp_f32_e32 v87, v9
	v_sub_f32_e32 v9, v35, v15
	v_mul_f32_e32 v9, 0x3fb8aa3b, v9
	v_exp_f32_e32 v88, v9
	v_sub_f32_e32 v9, v44, v15
	v_mul_f32_e32 v9, 0x3fb8aa3b, v9
	v_exp_f32_e32 v89, v9
	v_sub_f32_e32 v9, v45, v15
	v_mul_f32_e32 v9, 0x3fb8aa3b, v9
	v_exp_f32_e32 v90, v9
	v_sub_f32_e32 v9, v40, v15
	v_mul_f32_e32 v9, 0x3fb8aa3b, v9
	v_exp_f32_e32 v91, v9
	v_sub_f32_e32 v9, v41, v15
	v_mul_f32_e32 v9, 0x3fb8aa3b, v9
	v_exp_f32_e32 v92, v9
	v_sub_f32_e32 v9, v50, v15
	v_mul_f32_e32 v9, 0x3fb8aa3b, v9
	v_exp_f32_e32 v50, v9
	v_sub_f32_e32 v9, v51, v15
	v_mul_f32_e32 v9, 0x3fb8aa3b, v9
	v_exp_f32_e32 v51, v9
	v_sub_f32_e32 v9, v46, v15
	v_mul_f32_e32 v9, 0x3fb8aa3b, v9
	v_exp_f32_e32 v84, v9
	v_sub_f32_e32 v9, v47, v15
	v_sub_f32_e32 v4, v26, v15
	v_mul_f32_e32 v9, 0x3fb8aa3b, v9
	v_mul_f32_e32 v4, 0x3fb8aa3b, v4
	v_sub_f32_e32 v5, v27, v15
	v_exp_f32_e32 v47, v9
	v_sub_f32_e32 v9, v52, v15
	v_exp_f32_e32 v4, v4
	v_mul_f32_e32 v5, 0x3fb8aa3b, v5
	v_mul_f32_e32 v9, 0x3fb8aa3b, v9
	v_exp_f32_e32 v5, v5
	v_exp_f32_e32 v52, v9
	v_sub_f32_e32 v9, v53, v15
	v_mul_f32_e32 v9, 0x3fb8aa3b, v9
	v_exp_f32_e32 v53, v9
	v_sub_f32_e32 v9, v48, v15
	v_add_f32_e32 v8, 0, v4
	v_mul_f32_e32 v9, 0x3fb8aa3b, v9
	v_add_f32_e32 v8, v5, v8
	v_exp_f32_e32 v48, v9
	v_sub_f32_e32 v9, v49, v15
	v_add_f32_e32 v8, v93, v8
	v_mul_f32_e32 v9, 0x3fb8aa3b, v9
	v_add_f32_e32 v8, v95, v8
	v_exp_f32_e32 v49, v9
	v_sub_f32_e32 v9, v58, v15
	v_add_f32_e32 v8, v96, v8
	v_mul_f32_e32 v9, 0x3fb8aa3b, v9
	v_add_f32_e32 v8, v99, v8
	v_exp_f32_e32 v39, v9
	v_sub_f32_e32 v9, v59, v15
	v_add_f32_e32 v8, v101, v8
	v_mul_f32_e32 v9, 0x3fb8aa3b, v9
	v_add_f32_e32 v8, v103, v8
	v_exp_f32_e32 v40, v9
	v_sub_f32_e32 v9, v54, v15
	v_add_f32_e32 v8, v94, v8
	v_mul_f32_e32 v9, 0x3fb8aa3b, v9
	v_add_f32_e32 v8, v97, v8
	v_exp_f32_e32 v41, v9
	v_sub_f32_e32 v9, v55, v15
	v_add_f32_e32 v8, v98, v8
	v_mul_f32_e32 v9, 0x3fb8aa3b, v9
	v_add_f32_e32 v8, v100, v8
	v_exp_f32_e32 v42, v9
	v_sub_f32_e32 v9, v60, v15
	v_add_f32_e32 v8, v102, v8
	v_mul_f32_e32 v9, 0x3fb8aa3b, v9
	v_add_f32_e32 v8, v104, v8
	v_exp_f32_e32 v43, v9
	v_sub_f32_e32 v9, v61, v15
	v_add_f32_e32 v8, v105, v8
; __device__ __forceinline__ float ozero() { float z = 0.f; asm volatile("" : "+v"(z)); return z; }
; __device__ __forceinline__ void mem_attn(const Params& p, int layer, int task) {
;     ...
;   for (int kb = 0; kb < 16; kb++)
; #pragma unroll
;     for (int r = 0; r < 4; r++) { float e = __expf(st[kb][r] - mx); st[kb][r] = e; sum += e; }
;   sum += __shfl_xor(sum, 16); sum += __shfl_xor(sum, 32);
;   const float rinv = 1.f / sum;
;   f32x4 o[4];
; #pragma unroll
;   for (int mb = 0; mb < 4; mb++) { const float z_ = ozero(); o[mb] = (f32x4){z_, z_, z_, z_}; }
; #pragma unroll
;   for (int k2 = 0; k2 < 8; k2++) {
;     bf16x8 pf;
;     unsigned q0 = pk2(st[2 * k2][0], st[2 * k2][1]), q1 = pk2(st[2 * k2][2], st[2 * k2][3]);
;     unsigned q2 = pk2(st[2 * k2 + 1][0], st[2 * k2 + 1][1]), q3 = pk2(st[2 * k2 + 1][2], st[2 * k2 + 1][3]);
;     pf[0] = (short)(q0 & 0xFFFF); pf[1] = (short)(q0 >> 16); pf[2] = (short)(q1 & 0xFFFF); pf[3] = (short)(q1 >> 16);
;     pf[4] = (short)(q2 & 0xFFFF); pf[5] = (short)(q2 >> 16); pf[6] = (short)(q3 & 0xFFFF); pf[7] = (short)(q3 >> 16);
; #pragma unroll
;     for (int mb = 0; mb < 4; mb++) {
;       const bf* vp = mvt + (size_t)(16 * mb + n16) * 256 + 32 * k2 + 4 * kq;
;       uint2 v0 = *(const uint2*)vp, v1 = *(const uint2*)(vp + 16);
	v_mul_f32_e32 v9, 0x3fb8aa3b, v9
	v_add_f32_e32 v8, v106, v8
	v_exp_f32_e32 v44, v9
	v_sub_f32_e32 v9, v56, v15
	v_add_f32_e32 v8, v85, v8
	v_mul_f32_e32 v9, 0x3fb8aa3b, v9
	v_add_f32_e32 v8, v86, v8
	v_exp_f32_e32 v45, v9
	v_sub_f32_e32 v9, v57, v15
	v_add_f32_e32 v8, v87, v8
	v_mul_f32_e32 v9, 0x3fb8aa3b, v9
	v_add_f32_e32 v8, v88, v8
	v_exp_f32_e32 v46, v9
	v_sub_f32_e32 v9, v66, v15
	v_add_f32_e32 v8, v89, v8
	v_mul_f32_e32 v9, 0x3fb8aa3b, v9
	v_add_f32_e32 v8, v90, v8
	v_exp_f32_e32 v31, v9
	v_sub_f32_e32 v9, v67, v15
	v_add_f32_e32 v8, v91, v8
	v_mul_f32_e32 v9, 0x3fb8aa3b, v9
	v_add_f32_e32 v8, v92, v8
	v_exp_f32_e32 v32, v9
	v_sub_f32_e32 v9, v62, v15
	v_add_f32_e32 v8, v50, v8
	v_mul_f32_e32 v9, 0x3fb8aa3b, v9
	v_add_f32_e32 v8, v51, v8
	v_exp_f32_e32 v33, v9
	v_sub_f32_e32 v9, v63, v15
	v_add_f32_e32 v8, v84, v8
	v_mul_f32_e32 v9, 0x3fb8aa3b, v9
	v_add_f32_e32 v8, v47, v8
	v_exp_f32_e32 v34, v9
	v_sub_f32_e32 v9, v68, v15
	v_add_f32_e32 v8, v52, v8
	v_mul_f32_e32 v9, 0x3fb8aa3b, v9
	v_add_f32_e32 v8, v53, v8
	v_exp_f32_e32 v35, v9
	v_sub_f32_e32 v9, v69, v15
	v_add_f32_e32 v8, v48, v8
	v_mul_f32_e32 v9, 0x3fb8aa3b, v9
	v_add_f32_e32 v8, v49, v8
	v_exp_f32_e32 v36, v9
	v_sub_f32_e32 v9, v64, v15
	v_add_f32_e32 v8, v39, v8
	v_mul_f32_e32 v9, 0x3fb8aa3b, v9
	v_add_f32_e32 v8, v40, v8
	v_exp_f32_e32 v37, v9
	v_sub_f32_e32 v9, v65, v15
	v_add_f32_e32 v8, v41, v8
	v_mul_f32_e32 v9, 0x3fb8aa3b, v9
	v_add_f32_e32 v8, v42, v8
	v_exp_f32_e32 v38, v9
	v_sub_f32_e32 v9, v72, v15
	v_add_f32_e32 v8, v43, v8
	v_mul_f32_e32 v9, 0x3fb8aa3b, v9
	v_add_f32_e32 v8, v44, v8
	v_exp_f32_e32 v23, v9
	v_sub_f32_e32 v9, v73, v15
	v_add_f32_e32 v8, v45, v8
	v_mul_f32_e32 v9, 0x3fb8aa3b, v9
	v_add_f32_e32 v8, v46, v8
	v_exp_f32_e32 v24, v9
	v_sub_f32_e32 v9, v70, v15
	v_add_f32_e32 v8, v31, v8
	v_mul_f32_e32 v9, 0x3fb8aa3b, v9
	v_add_f32_e32 v8, v32, v8
	v_exp_f32_e32 v25, v9
	v_sub_f32_e32 v9, v71, v15
	v_add_f32_e32 v8, v33, v8
	v_mul_f32_e32 v9, 0x3fb8aa3b, v9
	v_add_f32_e32 v8, v34, v8
	v_exp_f32_e32 v26, v9
	v_sub_f32_e32 v9, v76, v15
	v_add_f32_e32 v8, v35, v8
	v_mul_f32_e32 v9, 0x3fb8aa3b, v9
	v_add_f32_e32 v8, v36, v8
	v_exp_f32_e32 v27, v9
	v_sub_f32_e32 v9, v77, v15
	v_add_f32_e32 v8, v37, v8
	v_mul_f32_e32 v9, 0x3fb8aa3b, v9
	v_add_f32_e32 v8, v38, v8
	v_exp_f32_e32 v28, v9
	v_sub_f32_e32 v9, v74, v15
	v_add_f32_e32 v8, v23, v8
	v_mul_f32_e32 v9, 0x3fb8aa3b, v9
	v_add_f32_e32 v8, v24, v8
	v_exp_f32_e32 v29, v9
	v_sub_f32_e32 v9, v75, v15
	v_add_f32_e32 v8, v25, v8
	v_mul_f32_e32 v9, 0x3fb8aa3b, v9
	v_add_f32_e32 v8, v26, v8
	v_exp_f32_e32 v30, v9
	v_add_f32_e32 v8, v27, v8
	v_add_f32_e32 v8, v28, v8
	v_add_f32_e32 v8, v29, v8
	v_add_f32_e32 v9, v30, v8
	v_sub_f32_e32 v8, v80, v15
	v_mul_f32_e32 v8, 0x3fb8aa3b, v8
	v_exp_f32_e32 v8, v8
	v_sub_f32_e32 v2, v2, v15
	v_mul_f32_e32 v2, 0x3fb8aa3b, v2
	v_sub_f32_e32 v3, v3, v15
	v_add_f32_e32 v10, v8, v9
	v_sub_f32_e32 v9, v81, v15
	v_mul_f32_e32 v9, 0x3fb8aa3b, v9
	v_exp_f32_e32 v9, v9
	v_mul_f32_e32 v3, 0x3fb8aa3b, v3
	v_sub_f32_e32 v0, v0, v15
	v_mul_f32_e32 v0, 0x3fb8aa3b, v0
	v_add_f32_e32 v11, v9, v10
	v_sub_f32_e32 v10, v78, v15
	v_mul_f32_e32 v10, 0x3fb8aa3b, v10
	v_exp_f32_e32 v10, v10
	v_sub_f32_e32 v1, v1, v15
	v_exp_f32_e32 v14, v0
	v_mul_f32_e32 v1, 0x3fb8aa3b, v1
	v_add_f32_e32 v12, v10, v11
	v_sub_f32_e32 v11, v79, v15
	v_mul_f32_e32 v11, 0x3fb8aa3b, v11
	v_exp_f32_e32 v11, v11
	v_exp_f32_e32 v15, v1
	v_mov_b32_e32 v54, v145
	v_mov_b32_e32 v58, v145
	v_add_f32_e32 v13, v11, v12
	v_exp_f32_e32 v12, v2
	v_mov_b32_e32 v62, v145
	v_mov_b32_e32 v66, v145
	v_add_f32_e32 v2, v12, v13
	v_exp_f32_e32 v13, v3
	v_cvt_pk_bf16_f32 v70, v4, v5
	v_add_f32_e32 v2, v13, v2
	v_add_f32_e32 v0, v14, v2
	v_add_f32_e32 v0, v15, v0
	ds_bpermute_b32 v1, v6, v0
	v_mov_b32_e32 v55, v54
	v_mov_b32_e32 v56, v54
	v_mov_b32_e32 v57, v54
	v_cvt_pk_bf16_f32 v71, v93, v95
	s_waitcnt lgkmcnt(0)
	v_add_f32_e32 v0, v0, v1
	ds_bpermute_b32 v1, v7, v0
	v_cvt_pk_bf16_f32 v72, v96, v99
	v_cvt_pk_bf16_f32 v73, v101, v103
	v_mov_b32_e32 v59, v58
	v_mov_b32_e32 v60, v58
	s_waitcnt lgkmcnt(0)
	v_add_f32_e32 v22, v0, v1
	v_lshl_add_u64 v[0:1], s[8:9], 0, v[144:145]
	v_lshl_add_u64 v[6:7], v[0:1], 0, v[18:19]
	v_lshlrev_b32_e32 v144, 9, v83
	v_lshl_add_u64 v[0:1], v[6:7], 0, v[144:145]
	v_mov_b32_e32 v200, 0x2000
	v_mov_b32_e32 v201, 0
	v_lshl_add_u64 v[146:147], v[0:1], 0, v[200:201]
	v_lshl_add_u64 v[196:197], v[146:147], 0, v[200:201]
	v_lshl_add_u64 v[198:199], v[196:197], 0, v[200:201]
	v_mov_b32_e32 v200, v0
	v_mov_b32_e32 v201, v1
	global_load_dwordx2 v[108:109], v[200:201], off
	global_load_dwordx2 v[110:111], v[200:201], off offset:32
	global_load_dwordx2 v[112:113], v[146:147], off
	global_load_dwordx2 v[114:115], v[146:147], off offset:32
	global_load_dwordx2 v[116:117], v[196:197], off
	global_load_dwordx2 v[118:119], v[196:197], off offset:32
	global_load_dwordx2 v[120:121], v[198:199], off
	global_load_dwordx2 v[122:123], v[198:199], off offset:32
	global_load_dwordx2 v[124:125], v[200:201], off offset:64
	global_load_dwordx2 v[126:127], v[200:201], off offset:96
	global_load_dwordx2 v[128:129], v[146:147], off offset:64
	global_load_dwordx2 v[130:131], v[146:147], off offset:96
	global_load_dwordx2 v[132:133], v[196:197], off offset:64
	global_load_dwordx2 v[134:135], v[196:197], off offset:96
	global_load_dwordx2 v[136:137], v[198:199], off offset:64
	global_load_dwordx2 v[138:139], v[198:199], off offset:96
	global_load_dwordx2 v[140:141], v[200:201], off offset:128
	global_load_dwordx2 v[142:143], v[200:201], off offset:160
	global_load_dwordx2 v[148:149], v[146:147], off offset:128
; __device__ __forceinline__ f32x4 mfma16(bf16x8 a, bf16x8 b, f32x4 c) { return __builtin_amdgcn_mfma_f32_16x16x32_bf16(a, b, c, 0, 0, 0); }
; __device__ __forceinline__ void mem_attn(const Params& p, int layer, int task) {
;     ...
;   for (int k2 = 0; k2 < 8; k2++) {
;     bf16x8 pf;
;     unsigned q0 = pk2(st[2 * k2][0], st[2 * k2][1]), q1 = pk2(st[2 * k2][2], st[2 * k2][3]);
;     unsigned q2 = pk2(st[2 * k2 + 1][0], st[2 * k2 + 1][1]), q3 = pk2(st[2 * k2 + 1][2], st[2 * k2 + 1][3]);
;     pf[0] = (short)(q0 & 0xFFFF); pf[1] = (short)(q0 >> 16); pf[2] = (short)(q1 & 0xFFFF); pf[3] = (short)(q1 >> 16);
;     pf[4] = (short)(q2 & 0xFFFF); pf[5] = (short)(q2 >> 16); pf[6] = (short)(q3 & 0xFFFF); pf[7] = (short)(q3 >> 16);
; #pragma unroll
;     for (int mb = 0; mb < 4; mb++) {
;       const bf* vp = mvt + (size_t)(16 * mb + n16) * 256 + 32 * k2 + 4 * kq;
;       uint2 v0 = *(const uint2*)vp, v1 = *(const uint2*)(vp + 16);
;       bf16x8 af;
;       af[0] = (short)(v0.x & 0xFFFF); af[1] = (short)(v0.x >> 16); af[2] = (short)(v0.y & 0xFFFF); af[3] = (short)(v0.y >> 16);
;       af[4] = (short)(v1.x & 0xFFFF); af[5] = (short)(v1.x >> 16); af[6] = (short)(v1.y & 0xFFFF); af[7] = (short)(v1.y >> 16);
;       o[mb] = mfma16(af, pf, o[mb]);
;     }
	global_load_dwordx2 v[150:151], v[146:147], off offset:160
	global_load_dwordx2 v[152:153], v[196:197], off offset:128
	global_load_dwordx2 v[154:155], v[196:197], off offset:160
	global_load_dwordx2 v[156:157], v[198:199], off offset:128
	global_load_dwordx2 v[158:159], v[198:199], off offset:160
	global_load_dwordx2 v[160:161], v[200:201], off offset:192
	global_load_dwordx2 v[162:163], v[200:201], off offset:224
	global_load_dwordx2 v[164:165], v[146:147], off offset:192
	global_load_dwordx2 v[166:167], v[146:147], off offset:224
	global_load_dwordx2 v[168:169], v[196:197], off offset:192
	global_load_dwordx2 v[170:171], v[196:197], off offset:224
	global_load_dwordx2 v[172:173], v[198:199], off offset:192
	global_load_dwordx2 v[174:175], v[198:199], off offset:224
	global_load_dwordx2 v[176:177], v[200:201], off offset:256
	global_load_dwordx2 v[178:179], v[200:201], off offset:288
	global_load_dwordx2 v[180:181], v[146:147], off offset:256
	global_load_dwordx2 v[182:183], v[146:147], off offset:288
	global_load_dwordx2 v[184:185], v[196:197], off offset:256
	global_load_dwordx2 v[186:187], v[196:197], off offset:288
	global_load_dwordx2 v[188:189], v[198:199], off offset:256
	global_load_dwordx2 v[190:191], v[198:199], off offset:288
	global_load_dwordx2 v[192:193], v[200:201], off offset:320
	global_load_dwordx2 v[194:195], v[200:201], off offset:352
	v_mov_b32_e32 v61, v58
	v_mov_b32_e32 v63, v62
	v_mov_b32_e32 v64, v62
	v_mov_b32_e32 v65, v62
	v_mov_b32_e32 v67, v66
	v_mov_b32_e32 v68, v66
	v_mov_b32_e32 v69, v66
	v_lshl_add_u64 v[78:79], v[6:7], 0, 64
	v_cvt_pk_bf16_f32 v50, v50, v51
	v_cvt_pk_bf16_f32 v51, v84, v47
	v_cvt_pk_bf16_f32 v52, v52, v53
	v_cvt_pk_bf16_f32 v53, v48, v49
	v_lshl_add_u64 v[48:49], v[6:7], 0, s[0:1]
	v_cvt_pk_bf16_f32 v41, v41, v42
	v_cvt_pk_bf16_f32 v42, v43, v44
	v_cvt_pk_bf16_f32 v43, v45, v46
	v_cvt_pk_bf16_f32 v40, v39, v40
	v_cvt_pk_bf16_f32 v33, v33, v34
	v_cvt_pk_bf16_f32 v34, v35, v36
	v_cvt_pk_bf16_f32 v35, v37, v38
	s_mov_b64 s[0:1], 0x140
	v_cvt_pk_bf16_f32 v32, v31, v32
	v_cvt_pk_bf16_f32 v25, v25, v26
	v_cvt_pk_bf16_f32 v26, v27, v28
	v_cvt_pk_bf16_f32 v27, v29, v30
	v_cvt_pk_bf16_f32 v24, v23, v24
	s_nop 0
	s_nop 1
	s_waitcnt vmcnt(40)
	v_mfma_f32_16x16x32_bf16 v[54:57], v[108:111], v[70:73], v[54:57]
	global_load_dwordx2 v[108:109], v[146:147], off offset:320
	global_load_dwordx2 v[110:111], v[146:147], off offset:352
	v_or_b32_e32 v2, 0x2000, v144
	v_mov_b32_e32 v3, v145
	v_lshl_add_u64 v[4:5], v[6:7], 0, v[2:3]
	v_or_b32_e32 v4, 0x4000, v144
	v_mov_b32_e32 v5, v145
	v_or_b32_e32 v144, 0x6000, v144
	s_nop 0
	s_nop 1
	s_waitcnt vmcnt(40)
	v_mfma_f32_16x16x32_bf16 v[58:61], v[112:115], v[70:73], v[58:61]
	global_load_dwordx2 v[112:113], v[196:197], off offset:320
	global_load_dwordx2 v[114:115], v[196:197], off offset:352
	v_lshl_add_u64 v[76:77], v[6:7], 0, v[4:5]
	s_nop 0
	s_nop 0
	s_nop 1
	s_waitcnt vmcnt(40)
	v_mfma_f32_16x16x32_bf16 v[62:65], v[116:119], v[70:73], v[62:65]
	global_load_dwordx2 v[116:117], v[198:199], off offset:320
	global_load_dwordx2 v[118:119], v[198:199], off offset:352
	v_lshl_add_u64 v[76:77], v[6:7], 0, v[144:145]
	s_nop 0
	s_nop 0
	s_nop 1
	s_waitcnt vmcnt(40)
	v_mfma_f32_16x16x32_bf16 v[66:69], v[120:123], v[70:73], v[66:69]
	global_load_dwordx2 v[120:121], v[200:201], off offset:384
	global_load_dwordx2 v[122:123], v[200:201], off offset:416
	v_cvt_pk_bf16_f32 v70, v94, v97
	v_cvt_pk_bf16_f32 v71, v98, v100
	v_cvt_pk_bf16_f32 v72, v102, v104
	v_cvt_pk_bf16_f32 v73, v105, v106
	s_nop 0
	s_nop 1
	s_waitcnt vmcnt(40)
	v_mfma_f32_16x16x32_bf16 v[54:57], v[124:127], v[70:73], v[54:57]
	global_load_dwordx2 v[124:125], v[146:147], off offset:384
	global_load_dwordx2 v[126:127], v[146:147], off offset:416
	v_lshl_add_u64 v[76:77], v[78:79], 0, v[2:3]
	s_nop 0
	s_nop 0
	s_nop 1
	s_waitcnt vmcnt(40)
	v_mfma_f32_16x16x32_bf16 v[58:61], v[128:131], v[70:73], v[58:61]
	global_load_dwordx2 v[128:129], v[196:197], off offset:384
	global_load_dwordx2 v[130:131], v[196:197], off offset:416
	v_lshl_add_u64 v[76:77], v[78:79], 0, v[4:5]
	s_nop 0
	s_nop 0
	s_nop 1
	s_waitcnt vmcnt(40)
	v_mfma_f32_16x16x32_bf16 v[62:65], v[132:135], v[70:73], v[62:65]
	global_load_dwordx2 v[132:133], v[198:199], off offset:384
	global_load_dwordx2 v[134:135], v[198:199], off offset:416
	v_lshl_add_u64 v[76:77], v[78:79], 0, v[144:145]
	s_nop 0
	v_lshl_add_u64 v[78:79], v[6:7], 0, s[50:51]
	s_nop 0
	s_nop 1
	s_waitcnt vmcnt(40)
	v_mfma_f32_16x16x32_bf16 v[66:69], v[136:139], v[70:73], v[66:69]
	global_load_dwordx2 v[136:137], v[200:201], off offset:448
	global_load_dwordx2 v[138:139], v[200:201], off offset:480
	v_cvt_pk_bf16_f32 v70, v85, v86
	v_cvt_pk_bf16_f32 v71, v87, v88
	v_cvt_pk_bf16_f32 v72, v89, v90
	v_cvt_pk_bf16_f32 v73, v91, v92
	s_nop 0
	s_nop 1
	s_waitcnt vmcnt(40)
	v_mfma_f32_16x16x32_bf16 v[54:57], v[140:143], v[70:73], v[54:57]
	global_load_dwordx2 v[140:141], v[146:147], off offset:448
	global_load_dwordx2 v[142:143], v[146:147], off offset:480
	v_lshl_add_u64 v[76:77], v[78:79], 0, v[2:3]
	s_nop 0
	s_nop 0
	s_nop 1
	s_waitcnt vmcnt(40)
	v_mfma_f32_16x16x32_bf16 v[58:61], v[148:151], v[70:73], v[58:61]
	global_load_dwordx2 v[148:149], v[196:197], off offset:448
	global_load_dwordx2 v[150:151], v[196:197], off offset:480
	v_lshl_add_u64 v[76:77], v[78:79], 0, v[4:5]
	s_nop 0
	s_nop 0
	s_nop 1
	s_waitcnt vmcnt(40)
	v_mfma_f32_16x16x32_bf16 v[62:65], v[152:155], v[70:73], v[62:65]
	global_load_dwordx2 v[152:153], v[198:199], off offset:448
	global_load_dwordx2 v[154:155], v[198:199], off offset:480
	v_lshl_add_u64 v[76:77], v[78:79], 0, v[144:145]
	s_nop 0
	s_nop 0
	s_nop 1
	s_waitcnt vmcnt(40)
; __device__ __forceinline__ float ozero() { float z = 0.f; asm volatile("" : "+v"(z)); return z; }
; __device__ __forceinline__ float bflo(unsigned u) { return __uint_as_float(u << 16); }
; __device__ __forceinline__ float bfhi(unsigned u) { return __uint_as_float(u & 0xFFFF0000u); }
; __device__ __forceinline__ float siluf_(float x) { return x * __builtin_amdgcn_rcpf(1.f + __expf(-x)); }
; __device__ __forceinline__ f32x4 mfma16(bf16x8 a, bf16x8 b, f32x4 c) { return __builtin_amdgcn_mfma_f32_16x16x32_bf16(a, b, c, 0, 0, 0); }
; __device__ __forceinline__ void mem_attn(const Params& p, int layer, int task) {
;     ...
;   const float rinv = 1.f / sum;
;   f32x4 o[4];
; #pragma unroll
;   for (int mb = 0; mb < 4; mb++) { const float z_ = ozero(); o[mb] = (f32x4){z_, z_, z_, z_}; }
; #pragma unroll
;   for (int k2 = 0; k2 < 8; k2++) {
;     bf16x8 pf;
;     unsigned q0 = pk2(st[2 * k2][0], st[2 * k2][1]), q1 = pk2(st[2 * k2][2], st[2 * k2][3]);
;     unsigned q2 = pk2(st[2 * k2 + 1][0], st[2 * k2 + 1][1]), q3 = pk2(st[2 * k2 + 1][2], st[2 * k2 + 1][3]);
;     pf[0] = (short)(q0 & 0xFFFF); pf[1] = (short)(q0 >> 16); pf[2] = (short)(q1 & 0xFFFF); pf[3] = (short)(q1 >> 16);
;     pf[4] = (short)(q2 & 0xFFFF); pf[5] = (short)(q2 >> 16); pf[6] = (short)(q3 & 0xFFFF); pf[7] = (short)(q3 >> 16);
; #pragma unroll
;     for (int mb = 0; mb < 4; mb++) {
;       const bf* vp = mvt + (size_t)(16 * mb + n16) * 256 + 32 * k2 + 4 * kq;
;       uint2 v0 = *(const uint2*)vp, v1 = *(const uint2*)(vp + 16);
;       bf16x8 af;
;       af[0] = (short)(v0.x & 0xFFFF); af[1] = (short)(v0.x >> 16); af[2] = (short)(v0.y & 0xFFFF); af[3] = (short)(v0.y >> 16);
;       af[4] = (short)(v1.x & 0xFFFF); af[5] = (short)(v1.x >> 16); af[6] = (short)(v1.y & 0xFFFF); af[7] = (short)(v1.y >> 16);
;       o[mb] = mfma16(af, pf, o[mb]);
;     }
;   }
;   const size_t tok = tok0 + n16;
; #pragma unroll
;   for (int mb = 0; mb < 4; mb++) {
;     const int d = 16 * mb + 4 * kq;
;     uint2 zz = *(const uint2*)(p.P + tok * PW + C_MEZ + h * 64 + d);
;     float v0 = o[mb][0] * rinv * siluf_(bflo(zz.x)), v1 = o[mb][1] * rinv * siluf_(bfhi(zz.x));
;     float v2 = o[mb][2] * rinv * siluf_(bflo(zz.y)), v3 = o[mb][3] * rinv * siluf_(bfhi(zz.y));
;     *(uint2*)(p.Y + tok * YW + Y_MEM + h * 64 + d) = make_uint2(pk2(v0, v1), pk2(v2, v3));
	v_mfma_f32_16x16x32_bf16 v[66:69], v[156:159], v[70:73], v[66:69]
	s_nop 0
	s_nop 1
	s_waitcnt vmcnt(38)
	v_mfma_f32_16x16x32_bf16 v[54:57], v[160:163], v[50:53], v[54:57]
	v_lshl_add_u64 v[72:73], v[48:49], 0, v[2:3]
	s_nop 0
	s_nop 0
	s_nop 1
	s_waitcnt vmcnt(36)
	v_mfma_f32_16x16x32_bf16 v[58:61], v[164:167], v[50:53], v[58:61]
	v_lshl_add_u64 v[72:73], v[48:49], 0, v[4:5]
	s_nop 0
	v_lshl_add_u64 v[48:49], v[48:49], 0, v[144:145]
	s_nop 0
	s_nop 1
	s_waitcnt vmcnt(34)
	v_mfma_f32_16x16x32_bf16 v[62:65], v[168:171], v[50:53], v[62:65]
	s_nop 0
	s_nop 0
	s_waitcnt vmcnt(32)
	v_mfma_f32_16x16x32_bf16 v[48:51], v[172:175], v[50:53], v[66:69]
	s_nop 2
	v_lshl_add_u64 v[66:67], v[6:7], 0, s[70:71]
	s_waitcnt vmcnt(30)
	v_mfma_f32_16x16x32_bf16 v[44:47], v[176:179], v[40:43], v[54:57]
	s_nop 2
	v_lshl_add_u64 v[54:55], v[66:67], 0, v[2:3]
	s_nop 0
	s_nop 0
	s_nop 1
	s_waitcnt vmcnt(28)
	v_mfma_f32_16x16x32_bf16 v[52:55], v[180:183], v[40:43], v[58:61]
	s_nop 2
	v_lshl_add_u64 v[58:59], v[66:67], 0, v[4:5]
	s_nop 0
	s_nop 0
	s_nop 1
	s_waitcnt vmcnt(26)
	v_mfma_f32_16x16x32_bf16 v[56:59], v[184:187], v[40:43], v[62:65]
	s_nop 2
	v_lshl_add_u64 v[62:63], v[66:67], 0, v[144:145]
	s_nop 0
	s_nop 0
	s_nop 0
	s_nop 0
	s_waitcnt vmcnt(24)
	v_mfma_f32_16x16x32_bf16 v[40:43], v[188:191], v[40:43], v[48:51]
	v_lshl_add_u64 v[60:61], v[6:7], 0, s[0:1]
	s_nop 1
	v_lshl_add_u64 v[50:51], v[60:61], 0, v[4:5]
	s_mov_b64 s[0:1], 0x1c0
	s_waitcnt vmcnt(22)
	v_mfma_f32_16x16x32_bf16 v[36:39], v[192:195], v[32:35], v[44:47]
	s_nop 2
	v_lshl_add_u64 v[46:47], v[60:61], 0, v[2:3]
	s_nop 0
	s_nop 0
	s_nop 0
	s_nop 0
	s_nop 1
	s_waitcnt vmcnt(20)
	v_mfma_f32_16x16x32_bf16 v[44:47], v[108:111], v[32:35], v[52:55]
	s_nop 2
	v_lshl_add_u64 v[54:55], v[60:61], 0, v[144:145]
	s_nop 0
	s_nop 0
	s_nop 0
	s_nop 0
	s_nop 0
	s_waitcnt vmcnt(18)
	v_mfma_f32_16x16x32_bf16 v[48:51], v[112:115], v[32:35], v[56:59]
	s_waitcnt vmcnt(16)
	v_mfma_f32_16x16x32_bf16 v[32:35], v[116:119], v[32:35], v[40:43]
	v_lshl_add_u64 v[52:53], v[6:7], 0, s[72:73]
	s_waitcnt vmcnt(14)
	v_mfma_f32_16x16x32_bf16 v[28:31], v[120:123], v[24:27], v[36:39]
	s_nop 0
	v_lshl_add_u64 v[42:43], v[52:53], 0, v[4:5]
	s_nop 0
	v_lshl_add_u64 v[38:39], v[52:53], 0, v[2:3]
	s_nop 0
	s_nop 0
	s_nop 0
	s_nop 0
	s_nop 1
	s_waitcnt vmcnt(12)
	v_mfma_f32_16x16x32_bf16 v[36:39], v[124:127], v[24:27], v[44:47]
	s_nop 2
	v_lshl_add_u64 v[46:47], v[52:53], 0, v[144:145]
	s_nop 0
	s_nop 0
	s_nop 0
	s_waitcnt vmcnt(10)
	v_mfma_f32_16x16x32_bf16 v[40:43], v[128:131], v[24:27], v[48:51]
	s_nop 0
	s_waitcnt vmcnt(8)
	v_mfma_f32_16x16x32_bf16 v[24:27], v[132:135], v[24:27], v[32:35]
	v_lshl_add_u64 v[44:45], v[6:7], 0, s[0:1]
	v_lshl_add_u64 v[2:3], v[44:45], 0, v[2:3]
	v_div_scale_f32 v23, s[0:1], v22, v22, 1.0
	v_cvt_pk_bf16_f32 v32, v8, v9
	s_nop 0
	s_nop 0
	v_cvt_pk_bf16_f32 v33, v10, v11
	v_cvt_pk_bf16_f32 v34, v12, v13
	v_cvt_pk_bf16_f32 v35, v14, v15
	s_mov_b64 s[0:1], 0x2ac0
	s_nop 0
	s_nop 0
	s_waitcnt vmcnt(6)
	v_mfma_f32_16x16x32_bf16 v[12:15], v[136:139], v[32:35], v[28:31]
	s_nop 0
	s_waitcnt vmcnt(4)
	v_mfma_f32_16x16x32_bf16 v[8:11], v[140:143], v[32:35], v[36:39]
	v_lshl_add_u64 v[2:3], v[44:45], 0, v[4:5]
	s_nop 0
	s_nop 0
	s_nop 1
	s_waitcnt vmcnt(2)
	v_mfma_f32_16x16x32_bf16 v[4:7], v[148:151], v[32:35], v[40:43]
	v_lshl_add_u64 v[2:3], v[44:45], 0, v[144:145]
	s_nop 0
	s_nop 0
	s_nop 1
	s_waitcnt vmcnt(0)
	v_mfma_f32_16x16x32_bf16 v[0:3], v[152:155], v[32:35], v[24:27]
	s_nop 2
	v_rcp_f32_e32 v24, v23
	s_nop 0
	v_fma_f32 v25, -v23, v24, 1.0
	v_fmac_f32_e32 v24, v25, v24
	v_div_scale_f32 v25, vcc, 1.0, v22, 1.0
	v_mul_f32_e32 v26, v25, v24
	v_fma_f32 v27, -v23, v26, v25
	v_fmac_f32_e32 v26, v27, v24
	v_fma_f32 v23, -v23, v26, v25
	v_div_fmas_f32 v23, v23, v24, v26
	v_lshl_add_u64 v[24:25], v[20:21], 0, v[18:19]
	v_lshl_add_u64 v[20:21], v[24:25], 0, s[0:1]
	v_add_co_u32_e32 v24, vcc, s2, v24
	v_div_fixup_f32 v22, v23, v22, 1.0
	s_nop 0
	v_addc_co_u32_e32 v25, vcc, 0, v25, vcc
	global_load_dwordx2 v[24:25], v[24:25], off offset:2752
	s_waitcnt vmcnt(0)
; __device__ __forceinline__ float bflo(unsigned u) { return __uint_as_float(u << 16); }
; __device__ __forceinline__ float bfhi(unsigned u) { return __uint_as_float(u & 0xFFFF0000u); }
; __device__ __forceinline__ float siluf_(float x) { return x * __builtin_amdgcn_rcpf(1.f + __expf(-x)); }
; __device__ __forceinline__ void mem_attn(const Params& p, int layer, int task) {
;     ...
;   const size_t tok = tok0 + n16;
; #pragma unroll
;   for (int mb = 0; mb < 4; mb++) {
;     const int d = 16 * mb + 4 * kq;
;     uint2 zz = *(const uint2*)(p.P + tok * PW + C_MEZ + h * 64 + d);
;     float v0 = o[mb][0] * rinv * siluf_(bflo(zz.x)), v1 = o[mb][1] * rinv * siluf_(bfhi(zz.x));
;     float v2 = o[mb][2] * rinv * siluf_(bflo(zz.y)), v3 = o[mb][3] * rinv * siluf_(bfhi(zz.y));
;     *(uint2*)(p.Y + tok * YW + Y_MEM + h * 64 + d) = make_uint2(pk2(v0, v1), pk2(v2, v3));
;   }
	v_lshlrev_b32_e32 v26, 16, v24
	v_mul_f32_e32 v23, 0xbfb8aa3b, v26
	v_exp_f32_e32 v23, v23
	v_and_b32_e32 v27, 0xffff0000, v24
	v_lshlrev_b32_e32 v24, 16, v25
	v_and_b32_e32 v25, 0xffff0000, v25
	v_add_f32_e32 v23, 1.0, v23
	v_rcp_f32_e32 v28, v23
	v_pk_mul_f32 v[12:13], v[22:23], v[12:13] op_sel_hi:[0,1]
	v_mul_f32_e32 v23, 0xbfb8aa3b, v27
	v_exp_f32_e32 v23, v23
	s_nop 0
	v_add_f32_e32 v23, 1.0, v23
	v_rcp_f32_e32 v29, v23
	v_mul_f32_e32 v23, 0xbfb8aa3b, v24
	v_exp_f32_e32 v23, v23
	v_pk_mul_f32 v[26:27], v[28:29], v[26:27]
	s_nop 0
	v_pk_mul_f32 v[12:13], v[12:13], v[26:27]
	v_add_f32_e32 v23, 1.0, v23
	v_rcp_f32_e32 v26, v23
	v_pk_mul_f32 v[14:15], v[22:23], v[14:15] op_sel_hi:[0,1]
	v_mul_f32_e32 v23, 0xbfb8aa3b, v25
	v_exp_f32_e32 v23, v23
	s_nop 0
	v_add_f32_e32 v23, 1.0, v23
	v_rcp_f32_e32 v27, v23
	v_pk_mul_f32 v[8:9], v[22:23], v[8:9] op_sel_hi:[0,1]
	v_pk_mul_f32 v[10:11], v[22:23], v[10:11] op_sel_hi:[0,1]
	v_pk_mul_f32 v[4:5], v[22:23], v[4:5] op_sel_hi:[0,1]
	v_pk_mul_f32 v[24:25], v[26:27], v[24:25]
	v_pk_mul_f32 v[6:7], v[22:23], v[6:7] op_sel_hi:[0,1]
	v_pk_mul_f32 v[14:15], v[14:15], v[24:25]
	v_cvt_pk_bf16_f32 v24, v12, v13
	v_mov_b64_e32 v[12:13], s[64:65]
	v_mad_u64_u32 v[12:13], s[0:1], v82, s97, v[12:13]
	v_lshl_add_u64 v[12:13], v[12:13], 0, v[16:17]
	v_cvt_pk_bf16_f32 v25, v14, v15
	v_lshl_add_u64 v[14:15], v[12:13], 0, v[18:19]
	s_mov_b64 s[0:1], 0x1000
	v_lshl_add_u64 v[12:13], v[14:15], 0, s[0:1]
	v_add_co_u32_e32 v14, vcc, s4, v14
	v_pk_mul_f32 v[0:1], v[22:23], v[0:1] op_sel_hi:[0,1]
	s_nop 0
	v_addc_co_u32_e32 v15, vcc, 0, v15, vcc
	global_store_dwordx2 v[14:15], v[24:25], off
	global_load_dwordx2 v[14:15], v[20:21], off offset:32
	v_pk_mul_f32 v[2:3], v[22:23], v[2:3] op_sel_hi:[0,1]
	s_mov_b64 s[0:1], 0
	s_waitcnt vmcnt(0)
	v_lshlrev_b32_e32 v16, 16, v14
	v_and_b32_e32 v17, 0xffff0000, v14
	v_mul_f32_e32 v14, 0xbfb8aa3b, v16
	v_exp_f32_e32 v14, v14
	s_nop 0
	v_add_f32_e32 v14, 1.0, v14
	v_rcp_f32_e32 v18, v14
	v_mul_f32_e32 v14, 0xbfb8aa3b, v17
	v_exp_f32_e32 v14, v14
	s_nop 0
	v_add_f32_e32 v14, 1.0, v14
	v_rcp_f32_e32 v19, v14
	v_lshlrev_b32_e32 v14, 16, v15
	v_and_b32_e32 v15, 0xffff0000, v15
	v_pk_mul_f32 v[16:17], v[18:19], v[16:17]
	s_nop 0
	v_pk_mul_f32 v[8:9], v[8:9], v[16:17]
	v_mul_f32_e32 v16, 0xbfb8aa3b, v14
	v_mul_f32_e32 v17, 0xbfb8aa3b, v15
	v_exp_f32_e32 v16, v16
	v_exp_f32_e32 v17, v17
	v_cvt_pk_bf16_f32 v8, v8, v9
	v_add_f32_e32 v16, 1.0, v16
	v_add_f32_e32 v17, 1.0, v17
	v_rcp_f32_e32 v16, v16
	v_rcp_f32_e32 v17, v17
	s_nop 0
	v_pk_mul_f32 v[14:15], v[16:17], v[14:15]
	s_nop 0
	v_pk_mul_f32 v[10:11], v[10:11], v[14:15]
	s_nop 0
	v_cvt_pk_bf16_f32 v9, v10, v11
	global_store_dwordx2 v[12:13], v[8:9], off offset:32
	global_load_dwordx2 v[8:9], v[20:21], off offset:64
	s_waitcnt vmcnt(0)
	v_lshlrev_b32_e32 v10, 16, v8
	v_and_b32_e32 v11, 0xffff0000, v8
	v_mul_f32_e32 v8, 0xbfb8aa3b, v10
	v_exp_f32_e32 v8, v8
	s_nop 0
	v_add_f32_e32 v8, 1.0, v8
	v_rcp_f32_e32 v14, v8
	v_mul_f32_e32 v8, 0xbfb8aa3b, v11
	v_exp_f32_e32 v8, v8
	s_nop 0
	v_add_f32_e32 v8, 1.0, v8
	v_rcp_f32_e32 v15, v8
	v_lshlrev_b32_e32 v8, 16, v9
	v_and_b32_e32 v9, 0xffff0000, v9
	v_pk_mul_f32 v[10:11], v[14:15], v[10:11]
	s_nop 0
	v_pk_mul_f32 v[4:5], v[4:5], v[10:11]
	v_mul_f32_e32 v10, 0xbfb8aa3b, v8
	v_mul_f32_e32 v11, 0xbfb8aa3b, v9
	v_exp_f32_e32 v10, v10
	v_exp_f32_e32 v11, v11
	v_cvt_pk_bf16_f32 v4, v4, v5
	v_add_f32_e32 v10, 1.0, v10
	v_add_f32_e32 v11, 1.0, v11
	v_rcp_f32_e32 v10, v10
	v_rcp_f32_e32 v11, v11
	s_nop 0
	v_pk_mul_f32 v[8:9], v[10:11], v[8:9]
	s_nop 0
	v_pk_mul_f32 v[6:7], v[6:7], v[8:9]
	s_nop 0
	v_cvt_pk_bf16_f32 v5, v6, v7
	global_store_dwordx2 v[12:13], v[4:5], off offset:64
	global_load_dwordx2 v[4:5], v[20:21], off offset:96
	s_waitcnt vmcnt(0)
	v_lshlrev_b32_e32 v6, 16, v4
	v_and_b32_e32 v7, 0xffff0000, v4
	v_mul_f32_e32 v4, 0xbfb8aa3b, v6
	v_exp_f32_e32 v4, v4
	s_nop 0
	v_add_f32_e32 v4, 1.0, v4
	v_rcp_f32_e32 v8, v4
	v_mul_f32_e32 v4, 0xbfb8aa3b, v7
	v_exp_f32_e32 v4, v4
	s_nop 0
	v_add_f32_e32 v4, 1.0, v4
	v_rcp_f32_e32 v9, v4
	v_lshlrev_b32_e32 v4, 16, v5
	v_and_b32_e32 v5, 0xffff0000, v5
	v_pk_mul_f32 v[6:7], v[8:9], v[6:7]
	s_nop 0
	v_pk_mul_f32 v[0:1], v[0:1], v[6:7]
	v_mul_f32_e32 v6, 0xbfb8aa3b, v4
	v_mul_f32_e32 v7, 0xbfb8aa3b, v5
	v_exp_f32_e32 v6, v6
	v_exp_f32_e32 v7, v7
	v_cvt_pk_bf16_f32 v0, v0, v1
	v_add_f32_e32 v6, 1.0, v6
	v_add_f32_e32 v7, 1.0, v7
	v_rcp_f32_e32 v6, v6
	v_rcp_f32_e32 v7, v7
	s_nop 0
	v_pk_mul_f32 v[4:5], v[6:7], v[4:5]
	s_nop 0
	v_pk_mul_f32 v[2:3], v[2:3], v[4:5]
	s_nop 0
	v_cvt_pk_bf16_f32 v1, v2, v3
	global_store_dwordx2 v[12:13], v[0:1], off offset:96
